# K-loop compute-segment head: s_setprio 1 moved before BAR1, redundant lgkmcnt wait removed (first MFMA issues right after the barrier)
# baseline (speedup 1.0000x reference)
; #define PG8_STAGE(bufoff, gbase, voff) do { _Pragma("unroll") for (int _i = 0; _i < 2; ++_i) \
;         __builtin_amdgcn_global_load_lds((const unsigned*)((const char*)(gbase) + (voff)[_i]), (PG8_LAS unsigned*)(lds + (bufoff) + ldsw + _i * 8192), 16, 0, 0); } while (0)
; #define PG8_LDA(dst, b, h) do { _Pragma("unroll") for (int m = 0; m < 4; ++m) _Pragma("unroll") for (int k = 0; k < 2; ++k) dst[m][k] = *(const PG8_LAS bf16x8*)(lds + PG8_SA(b, h) + aoff + m * 2048 + k * 1024); } while (0)
; #define PG8_LDB(dst, b, h) do { _Pragma("unroll") for (int n = 0; n < 2; ++n) _Pragma("unroll") for (int k = 0; k < 2; ++k) dst[n][k] = *(const PG8_LAS bf16x8*)(lds + PG8_SB(b, h) + boff + n * 2048 + k * 1024); } while (0)
; #define PG8_WAIT_V(n) asm volatile("s_waitcnt vmcnt(" #n ")" ::: "memory")
; #define PG8_WAIT_L(n) asm volatile("s_waitcnt lgkmcnt(" #n ")" ::: "memory")
; #define PG8_BAR __builtin_amdgcn_s_barrier()
; #define PG8_SCHED __builtin_amdgcn_sched_barrier(0)
; template <class Epi, class Sched, bool ALIGN_EPI = false, bool SP2 = false>
; __device__ __forceinline__ void gemm_phase(PG8_LAS unsigned char* lds, const Gemm g, const Sched& S, const Epi& E) {
;     ...
;         const bool has_next = S.next(ui + 1, nxt);
;         const char* nA = has_next ? (const char*)g.A + (size_t)nxt.pm * tstepA : cA; const char* nB = has_next ? (const char*)g.Bt + (size_t)nxt.pn * tstepB : cB;
;         for (int t = 0; t < nt; t += 2) {
;             const bool last = (t == nt - 2);
;             const char* a1 = cA + (size_t)(t + 1) * kstepA;
;             const char* a2 = last ? nA : cA + (size_t)(t + 2) * kstepA; const char* b2 = last ? nB : cB + (size_t)(t + 2) * kstepB;
;             const char* a3 = a2 + kstepA; const char* b3 = b2 + kstepB;
;             if (last && has_next) { S.a_ready(nxt); E.prefetch(nxt, ui + 1, tid); }
;             if constexpr (SP2) {
;             PG8_LDB(B0, 0, 0); PG8_LDB(B1, 0, 1); PG8_SCHED; PG8_LDA(At, 0, 0); PG8_STAGE(PG8_SA(1, 1), a1 + hstepA, voffA);
;             PG8_WAIT_V(8); PG8_WAIT_L(0); PG8_BAR; PG8_MMA(0, 0, At, B0); PG8_MMA(0, 1, At, B1); PG8_BAR; PG8_SCHED;
;             PG8_LDA(At, 0, 1); PG8_STAGE(PG8_SB(0, 0), b2, voffB); PG8_STAGE(PG8_SB(0, 1), b2 + hstepB, voffB); PG8_STAGE(PG8_SA(0, 0), a2, voffA);
;             PG8_WAIT_V(8); PG8_WAIT_L(0); PG8_BAR; PG8_MMA(1, 0, At, B0); PG8_MMA(1, 1, At, B1); PG8_BAR; PG8_SCHED;
.LBB0_505:
	s_add_u32 s31, s2, s45
	s_addc_u32 s36, s3, s44
	s_lshl_b32 s16, s80, 8
	v_add_u32_e32 v2, s16, v1
	v_ashrrev_i32_e32 v3, 31, v2
	v_add_u32_e32 v4, s16, v232
	s_lshl_b32 s16, s43, 10
	v_lshlrev_b64 v[2:3], 7, v[2:3]
	v_ashrrev_i32_e32 v5, 31, v4
	s_and_b32 s16, s16, 0x400
	v_lshlrev_b64 v[4:5], 7, v[4:5]
	s_waitcnt lgkmcnt(0)
	v_lshl_add_u64 v[130:131], v[196:197], 0, v[2:3]
	s_add_u32 s39, s14, 0x10000
	v_add_u32_e32 v134, s16, v240
	v_lshl_add_u64 v[132:133], v[196:197], 0, v[4:5]
	v_add_u32_e32 v135, s16, v241
	s_addc_u32 s50, s15, 0
	s_mov_b64 s[14:15], 0
	s_mov_b64 s[16:17], 0
	s_add_u32 s18, s14, 1
	s_addc_u32 s19, s15, 0
	s_lshl_b64 s[60:61], s[18:19], s48
	s_add_u32 s14, s14, 2
	s_addc_u32 s15, s15, 0
	s_lshl_b64 s[18:19], s[14:15], s48
	s_add_u32 s18, s2, s18
	s_addc_u32 s19, s3, s19
	s_and_b64 s[16:17], s[16:17], exec
	s_cselect_b32 s24, s52, s18
	s_cselect_b32 s25, s53, s19
	s_cselect_b32 s19, s55, s50
	s_cselect_b32 s18, s54, s39
	s_add_u32 s16, s24, s35
	s_addc_u32 s17, s25, 0
	s_add_u32 s20, s18, 0x8000
	s_addc_u32 s21, s19, 0
	s_add_i32 s51, 0, 0x10000
	s_add_i32 s72, 0, 0x14000
	v_add_u32_e32 v148, s51, v195
	v_add_u32_e32 v164, s72, v195
	s_waitcnt lgkmcnt(0)
	ds_read_b128 v[136:139], v148
	ds_read_b128 v[140:143], v148 offset:1024
	ds_read_b128 v[144:147], v148 offset:2048
	ds_read_b128 v[148:151], v148 offset:3072
	ds_read_b128 v[152:155], v164
	ds_read_b128 v[156:159], v164 offset:1024
	ds_read_b128 v[160:163], v164 offset:2048
	ds_read_b128 v[164:167], v164 offset:3072
	s_add_u32 s60, s31, s60
	s_addc_u32 s61, s36, s61
	v_lshl_add_u64 v[180:181], s[60:61], 0, v[184:185]
	s_add_i32 m0, s63, 0xc000
	ds_read_b128 v[168:171], v242
	ds_read_b128 v[172:175], v242 offset:1024
	ds_read_b128 v[176:179], v242 offset:2048
	ds_read_b128 v[200:203], v242 offset:3072
	ds_read_b128 v[204:207], v242 offset:4096
	ds_read_b128 v[208:211], v242 offset:5120
	ds_read_b128 v[212:215], v242 offset:6144
	ds_read_b128 v[244:247], v242 offset:7168
	global_load_lds_dwordx4 v[180:181], off
	v_lshl_add_u64 v[180:181], s[60:61], 0, v[188:189]
	s_add_i32 m0, s63, 0xe000
	s_nop 0
	global_load_lds_dwordx4 v[180:181], off
	s_waitcnt vmcnt(8)
	s_waitcnt lgkmcnt(0)
	s_setprio 1
	s_barrier
	v_mfma_f32_16x16x32_bf16 v[126:129], v[136:139], v[168:171], 0
	v_mfma_f32_16x16x32_bf16 v[118:121], v[144:147], v[168:171], 0
	v_mfma_f32_16x16x32_bf16 v[110:113], v[136:139], v[176:179], 0
	v_mfma_f32_16x16x32_bf16 v[102:105], v[144:147], v[176:179], 0
	v_mfma_f32_16x16x32_bf16 v[94:97], v[136:139], v[204:207], 0
	v_mfma_f32_16x16x32_bf16 v[86:89], v[144:147], v[204:207], 0
	v_mfma_f32_16x16x32_bf16 v[78:81], v[136:139], v[212:215], 0
	v_mfma_f32_16x16x32_bf16 v[70:73], v[144:147], v[212:215], 0
	v_mfma_f32_16x16x32_bf16 v[126:129], v[140:143], v[172:175], v[126:129]
	v_mfma_f32_16x16x32_bf16 v[118:121], v[148:151], v[172:175], v[118:121]
	v_mfma_f32_16x16x32_bf16 v[110:113], v[140:143], v[200:203], v[110:113]
	v_mfma_f32_16x16x32_bf16 v[102:105], v[148:151], v[200:203], v[102:105]
	v_mfma_f32_16x16x32_bf16 v[94:97], v[140:143], v[208:211], v[94:97]
	v_mfma_f32_16x16x32_bf16 v[86:89], v[148:151], v[208:211], v[86:89]
	v_mfma_f32_16x16x32_bf16 v[78:81], v[140:143], v[244:247], v[78:81]
	v_mfma_f32_16x16x32_bf16 v[70:73], v[148:151], v[244:247], v[70:73]
	s_setprio 0
	s_setprio 1
	v_mfma_f32_16x16x32_bf16 v[122:125], v[152:155], v[168:171], 0
	v_mfma_f32_16x16x32_bf16 v[114:117], v[160:163], v[168:171], 0
	v_mfma_f32_16x16x32_bf16 v[106:109], v[152:155], v[176:179], 0
	v_mfma_f32_16x16x32_bf16 v[98:101], v[160:163], v[176:179], 0
	v_mfma_f32_16x16x32_bf16 v[90:93], v[152:155], v[204:207], 0
	v_mfma_f32_16x16x32_bf16 v[82:85], v[160:163], v[204:207], 0
	v_mfma_f32_16x16x32_bf16 v[74:77], v[152:155], v[212:215], 0
	v_mfma_f32_16x16x32_bf16 v[66:69], v[160:163], v[212:215], 0
	v_mfma_f32_16x16x32_bf16 v[122:125], v[156:159], v[172:175], v[122:125]
	v_mfma_f32_16x16x32_bf16 v[114:117], v[164:167], v[172:175], v[114:117]
	v_mfma_f32_16x16x32_bf16 v[106:109], v[156:159], v[200:203], v[106:109]
	v_mfma_f32_16x16x32_bf16 v[98:101], v[164:167], v[200:203], v[98:101]
	v_mfma_f32_16x16x32_bf16 v[90:93], v[156:159], v[208:211], v[90:93]
	v_mfma_f32_16x16x32_bf16 v[82:85], v[164:167], v[208:211], v[82:85]
	s_setprio 2
	s_barrier
	v_mfma_f32_16x16x32_bf16 v[74:77], v[156:159], v[244:247], v[74:77]
	v_mfma_f32_16x16x32_bf16 v[66:69], v[164:167], v[244:247], v[66:69]
	s_setprio 0
	s_add_i32 s51, s51, s62
	v_lshl_add_u64 v[180:181], s[18:19], 0, v[186:187]
	s_mov_b32 m0, s51
	ds_read_b128 v[168:171], v242 offset:16384
	ds_read_b128 v[172:175], v242 offset:17408
	ds_read_b128 v[176:179], v242 offset:18432
	ds_read_b128 v[200:203], v242 offset:19456
	ds_read_b128 v[204:207], v242 offset:20480
	ds_read_b128 v[208:211], v242 offset:21504
	ds_read_b128 v[212:215], v242 offset:22528
	ds_read_b128 v[244:247], v242 offset:23552
	global_load_lds_dwordx4 v[180:181], off
	s_add_i32 m0, s51, 0x2000
	s_add_u32 s60, s18, 0x4000
	v_lshl_add_u64 v[180:181], s[18:19], 0, v[190:191]
	s_addc_u32 s61, s19, 0
	s_add_i32 s51, s72, s62
	global_load_lds_dwordx4 v[180:181], off
	v_lshl_add_u64 v[180:181], s[60:61], 0, v[186:187]
	s_mov_b32 m0, s51
	s_nop 0
	global_load_lds_dwordx4 v[180:181], off
	v_lshl_add_u64 v[180:181], s[60:61], 0, v[190:191]
	s_add_i32 m0, s51, 0x2000
	s_nop 0
	global_load_lds_dwordx4 v[180:181], off
	v_lshl_add_u64 v[180:181], s[24:25], 0, v[184:185]
	s_mov_b32 m0, s63
	s_nop 0
	global_load_lds_dwordx4 v[180:181], off
	v_lshl_add_u64 v[180:181], s[24:25], 0, v[188:189]
	s_mov_b32 m0, s28
	s_nop 0
	global_load_lds_dwordx4 v[180:181], off
	s_waitcnt vmcnt(8)
	s_waitcnt lgkmcnt(0)
	s_setprio 1
	s_barrier
; #define PG8_STAGE(bufoff, gbase, voff) do { _Pragma("unroll") for (int _i = 0; _i < 2; ++_i) \
;         __builtin_amdgcn_global_load_lds((const unsigned*)((const char*)(gbase) + (voff)[_i]), (PG8_LAS unsigned*)(lds + (bufoff) + ldsw + _i * 8192), 16, 0, 0); } while (0)
; #define PG8_LDA(dst, b, h) do { _Pragma("unroll") for (int m = 0; m < 4; ++m) _Pragma("unroll") for (int k = 0; k < 2; ++k) dst[m][k] = *(const PG8_LAS bf16x8*)(lds + PG8_SA(b, h) + aoff + m * 2048 + k * 1024); } while (0)
; #define PG8_LDB(dst, b, h) do { _Pragma("unroll") for (int n = 0; n < 2; ++n) _Pragma("unroll") for (int k = 0; k < 2; ++k) dst[n][k] = *(const PG8_LAS bf16x8*)(lds + PG8_SB(b, h) + boff + n * 2048 + k * 1024); } while (0)
; #define PG8_MMA(ai, bj, At, Bt) do { __builtin_amdgcn_s_setprio(1); _Pragma("unroll") for (int m = 0; m < 4; ++m) _Pragma("unroll") for (int n = 0; n < 2; ++n) _Pragma("unroll") for (int k = 0; k < 2; ++k) \
;         acc[ai][bj][m][n] = __builtin_amdgcn_mfma_f32_16x16x32_bf16(Bt[n][k], At[m][k], acc[ai][bj][m][n], 0, 0, 0); __builtin_amdgcn_s_setprio(0); } while (0)
; #define PG8_WAIT_V(n) asm volatile("s_waitcnt vmcnt(" #n ")" ::: "memory")
; #define PG8_WAIT_L(n) asm volatile("s_waitcnt lgkmcnt(" #n ")" ::: "memory")
; #define PG8_BAR __builtin_amdgcn_s_barrier()
; #define PG8_SCHED __builtin_amdgcn_sched_barrier(0)
; template <class Epi, class Sched, bool ALIGN_EPI = false, bool SP2 = false>
; __device__ __forceinline__ void gemm_phase(PG8_LAS unsigned char* lds, const Gemm g, const Sched& S, const Epi& E) {
;     ...
;             PG8_WAIT_V(8); PG8_WAIT_L(0); PG8_BAR; PG8_MMA(1, 0, At, B0); PG8_MMA(1, 1, At, B1); PG8_BAR; PG8_SCHED;
;             PG8_LDB(B0, 1, 0); PG8_LDB(B1, 1, 1); PG8_SCHED; PG8_LDA(At, 1, 0); PG8_STAGE(PG8_SA(0, 1), a2 + hstepA, voffA);
;             PG8_WAIT_V(8); PG8_WAIT_L(0); PG8_BAR; PG8_MMA(0, 0, At, B0); PG8_MMA(0, 1, At, B1); PG8_BAR; PG8_SCHED;
	v_mfma_f32_16x16x32_bf16 v[62:65], v[136:139], v[168:171], 0
	v_mfma_f32_16x16x32_bf16 v[54:57], v[144:147], v[168:171], 0
	v_mfma_f32_16x16x32_bf16 v[46:49], v[136:139], v[176:179], 0
	v_mfma_f32_16x16x32_bf16 v[38:41], v[144:147], v[176:179], 0
	v_mfma_f32_16x16x32_bf16 v[30:33], v[136:139], v[204:207], 0
	v_mfma_f32_16x16x32_bf16 v[22:25], v[144:147], v[204:207], 0
	v_mfma_f32_16x16x32_bf16 v[14:17], v[136:139], v[212:215], 0
	v_mfma_f32_16x16x32_bf16 v[6:9], v[144:147], v[212:215], 0
	v_mfma_f32_16x16x32_bf16 v[62:65], v[140:143], v[172:175], v[62:65]
	v_mfma_f32_16x16x32_bf16 v[54:57], v[148:151], v[172:175], v[54:57]
	v_mfma_f32_16x16x32_bf16 v[46:49], v[140:143], v[200:203], v[46:49]
	v_mfma_f32_16x16x32_bf16 v[38:41], v[148:151], v[200:203], v[38:41]
	v_mfma_f32_16x16x32_bf16 v[30:33], v[140:143], v[208:211], v[30:33]
	v_mfma_f32_16x16x32_bf16 v[22:25], v[148:151], v[208:211], v[22:25]
	v_mfma_f32_16x16x32_bf16 v[14:17], v[140:143], v[244:247], v[14:17]
	v_mfma_f32_16x16x32_bf16 v[6:9], v[148:151], v[244:247], v[6:9]
	s_setprio 0
	s_setprio 1
	v_mfma_f32_16x16x32_bf16 v[58:61], v[152:155], v[168:171], 0
	v_mfma_f32_16x16x32_bf16 v[50:53], v[160:163], v[168:171], 0
	v_mfma_f32_16x16x32_bf16 v[42:45], v[152:155], v[176:179], 0
	v_mfma_f32_16x16x32_bf16 v[34:37], v[160:163], v[176:179], 0
	v_mfma_f32_16x16x32_bf16 v[26:29], v[152:155], v[204:207], 0
	v_mfma_f32_16x16x32_bf16 v[18:21], v[160:163], v[204:207], 0
	v_mfma_f32_16x16x32_bf16 v[10:13], v[152:155], v[212:215], 0
	v_mfma_f32_16x16x32_bf16 v[2:5], v[160:163], v[212:215], 0
	v_mfma_f32_16x16x32_bf16 v[58:61], v[156:159], v[172:175], v[58:61]
	v_mfma_f32_16x16x32_bf16 v[50:53], v[164:167], v[172:175], v[50:53]
	v_mfma_f32_16x16x32_bf16 v[42:45], v[156:159], v[200:203], v[42:45]
	v_mfma_f32_16x16x32_bf16 v[34:37], v[164:167], v[200:203], v[34:37]
	v_mfma_f32_16x16x32_bf16 v[26:29], v[156:159], v[208:211], v[26:29]
	v_mfma_f32_16x16x32_bf16 v[18:21], v[164:167], v[208:211], v[18:21]
	s_setprio 2
	s_barrier
	v_mfma_f32_16x16x32_bf16 v[10:13], v[156:159], v[244:247], v[10:13]
	v_mfma_f32_16x16x32_bf16 v[2:5], v[164:167], v[244:247], v[2:5]
	s_setprio 0
	s_add_i32 s51, 0, 0x18000
	s_add_i32 s60, 0, 0x1c000
	v_add_u32_e32 v148, s51, v195
	v_add_u32_e32 v164, s60, v195
	ds_read_b128 v[136:139], v148
	ds_read_b128 v[140:143], v148 offset:1024
	ds_read_b128 v[144:147], v148 offset:2048
	ds_read_b128 v[148:151], v148 offset:3072
	ds_read_b128 v[152:155], v164
	ds_read_b128 v[156:159], v164 offset:1024
	ds_read_b128 v[160:163], v164 offset:2048
	ds_read_b128 v[164:167], v164 offset:3072
	s_add_u32 s24, s24, s45
	s_addc_u32 s25, s25, s44
	s_mov_b32 m0, s29
	v_lshl_add_u64 v[180:181], s[24:25], 0, v[184:185]
	ds_read_b128 v[168:171], v242 offset:32768
	ds_read_b128 v[172:175], v242 offset:33792
	ds_read_b128 v[176:179], v242 offset:34816
	ds_read_b128 v[200:203], v242 offset:35840
	ds_read_b128 v[204:207], v242 offset:36864
	ds_read_b128 v[208:211], v242 offset:37888
	ds_read_b128 v[212:215], v242 offset:38912
	ds_read_b128 v[244:247], v242 offset:39936
	global_load_lds_dwordx4 v[180:181], off
	v_lshl_add_u64 v[180:181], s[24:25], 0, v[188:189]
	s_mov_b32 m0, s26
	s_nop 0
	global_load_lds_dwordx4 v[180:181], off
	s_waitcnt vmcnt(8)
	s_waitcnt lgkmcnt(0)
	s_setprio 1
	s_barrier
	v_mfma_f32_16x16x32_bf16 v[126:129], v[136:139], v[168:171], v[126:129]
	v_mfma_f32_16x16x32_bf16 v[118:121], v[144:147], v[168:171], v[118:121]
	v_mfma_f32_16x16x32_bf16 v[110:113], v[136:139], v[176:179], v[110:113]
	v_mfma_f32_16x16x32_bf16 v[102:105], v[144:147], v[176:179], v[102:105]
	v_mfma_f32_16x16x32_bf16 v[94:97], v[136:139], v[204:207], v[94:97]
	v_mfma_f32_16x16x32_bf16 v[86:89], v[144:147], v[204:207], v[86:89]
	v_mfma_f32_16x16x32_bf16 v[78:81], v[136:139], v[212:215], v[78:81]
	v_mfma_f32_16x16x32_bf16 v[70:73], v[144:147], v[212:215], v[70:73]
	v_mfma_f32_16x16x32_bf16 v[126:129], v[140:143], v[172:175], v[126:129]
	v_mfma_f32_16x16x32_bf16 v[118:121], v[148:151], v[172:175], v[118:121]
	v_mfma_f32_16x16x32_bf16 v[110:113], v[140:143], v[200:203], v[110:113]
	v_mfma_f32_16x16x32_bf16 v[102:105], v[148:151], v[200:203], v[102:105]
	v_mfma_f32_16x16x32_bf16 v[94:97], v[140:143], v[208:211], v[94:97]
	v_mfma_f32_16x16x32_bf16 v[86:89], v[148:151], v[208:211], v[86:89]
	v_mfma_f32_16x16x32_bf16 v[78:81], v[140:143], v[244:247], v[78:81]
	v_mfma_f32_16x16x32_bf16 v[70:73], v[148:151], v[244:247], v[70:73]
	s_setprio 0
	s_setprio 1
	v_mfma_f32_16x16x32_bf16 v[122:125], v[152:155], v[168:171], v[122:125]
	v_mfma_f32_16x16x32_bf16 v[114:117], v[160:163], v[168:171], v[114:117]
	v_mfma_f32_16x16x32_bf16 v[106:109], v[152:155], v[176:179], v[106:109]
	v_mfma_f32_16x16x32_bf16 v[98:101], v[160:163], v[176:179], v[98:101]
	v_mfma_f32_16x16x32_bf16 v[90:93], v[152:155], v[204:207], v[90:93]
	v_mfma_f32_16x16x32_bf16 v[82:85], v[160:163], v[204:207], v[82:85]
	v_mfma_f32_16x16x32_bf16 v[74:77], v[152:155], v[212:215], v[74:77]
	v_mfma_f32_16x16x32_bf16 v[66:69], v[160:163], v[212:215], v[66:69]
	v_mfma_f32_16x16x32_bf16 v[122:125], v[156:159], v[172:175], v[122:125]
	v_mfma_f32_16x16x32_bf16 v[114:117], v[164:167], v[172:175], v[114:117]
	v_mfma_f32_16x16x32_bf16 v[106:109], v[156:159], v[200:203], v[106:109]
	v_mfma_f32_16x16x32_bf16 v[98:101], v[164:167], v[200:203], v[98:101]
	v_mfma_f32_16x16x32_bf16 v[90:93], v[156:159], v[208:211], v[90:93]
	v_mfma_f32_16x16x32_bf16 v[82:85], v[164:167], v[208:211], v[82:85]
	s_setprio 2
	s_barrier
; #define PG8_STAGE(bufoff, gbase, voff) do { _Pragma("unroll") for (int _i = 0; _i < 2; ++_i) \
;         __builtin_amdgcn_global_load_lds((const unsigned*)((const char*)(gbase) + (voff)[_i]), (PG8_LAS unsigned*)(lds + (bufoff) + ldsw + _i * 8192), 16, 0, 0); } while (0)
; #define PG8_LDA(dst, b, h) do { _Pragma("unroll") for (int m = 0; m < 4; ++m) _Pragma("unroll") for (int k = 0; k < 2; ++k) dst[m][k] = *(const PG8_LAS bf16x8*)(lds + PG8_SA(b, h) + aoff + m * 2048 + k * 1024); } while (0)
; #define PG8_MMA(ai, bj, At, Bt) do { __builtin_amdgcn_s_setprio(1); _Pragma("unroll") for (int m = 0; m < 4; ++m) _Pragma("unroll") for (int n = 0; n < 2; ++n) _Pragma("unroll") for (int k = 0; k < 2; ++k) \
;         acc[ai][bj][m][n] = __builtin_amdgcn_mfma_f32_16x16x32_bf16(Bt[n][k], At[m][k], acc[ai][bj][m][n], 0, 0, 0); __builtin_amdgcn_s_setprio(0); } while (0)
; #define PG8_WAIT_V(n) asm volatile("s_waitcnt vmcnt(" #n ")" ::: "memory")
; #define PG8_WAIT_L(n) asm volatile("s_waitcnt lgkmcnt(" #n ")" ::: "memory")
; #define PG8_BAR __builtin_amdgcn_s_barrier()
; #define PG8_SCHED __builtin_amdgcn_sched_barrier(0)
; template <class Epi, class Sched, bool ALIGN_EPI = false, bool SP2 = false>
; __device__ __forceinline__ void gemm_phase(PG8_LAS unsigned char* lds, const Gemm g, const Sched& S, const Epi& E) {
;     ...
;             PG8_LDA(At, 1, 1); PG8_STAGE(PG8_SB(1, 0), b3, voffB); PG8_STAGE(PG8_SB(1, 1), b3 + hstepB, voffB); PG8_STAGE(PG8_SA(1, 0), a3, voffA);
;             PG8_WAIT_V(8); PG8_WAIT_L(0); PG8_BAR; PG8_MMA(1, 0, At, B0); PG8_MMA(1, 1, At, B1); PG8_BAR; PG8_SCHED;
	v_mfma_f32_16x16x32_bf16 v[74:77], v[156:159], v[244:247], v[74:77]
	v_mfma_f32_16x16x32_bf16 v[66:69], v[164:167], v[244:247], v[66:69]
	s_setprio 0
	s_add_i32 s24, s51, s62
	v_lshl_add_u64 v[180:181], s[20:21], 0, v[186:187]
	s_mov_b32 m0, s24
	ds_read_b128 v[168:171], v242 offset:49152
	ds_read_b128 v[172:175], v242 offset:50176
	ds_read_b128 v[176:179], v242 offset:51200
	ds_read_b128 v[200:203], v242 offset:52224
	ds_read_b128 v[204:207], v242 offset:53248
	ds_read_b128 v[208:211], v242 offset:54272
	ds_read_b128 v[212:215], v242 offset:55296
	ds_read_b128 v[244:247], v242 offset:56320
	global_load_lds_dwordx4 v[180:181], off
	s_add_i32 m0, s24, 0x2000
	s_add_u32 s18, s18, 0xc000
	v_lshl_add_u64 v[180:181], s[20:21], 0, v[190:191]
	s_addc_u32 s19, s19, 0
	s_add_i32 s20, s60, s62
	global_load_lds_dwordx4 v[180:181], off
	v_lshl_add_u64 v[180:181], s[18:19], 0, v[186:187]
	s_mov_b32 m0, s20
	s_nop 0
	global_load_lds_dwordx4 v[180:181], off
	v_lshl_add_u64 v[180:181], s[18:19], 0, v[190:191]
	s_add_i32 m0, s20, 0x2000
	s_nop 0
	global_load_lds_dwordx4 v[180:181], off
	v_lshl_add_u64 v[180:181], s[16:17], 0, v[184:185]
	s_mov_b32 m0, s1
	s_nop 0
	global_load_lds_dwordx4 v[180:181], off
	v_lshl_add_u64 v[180:181], s[16:17], 0, v[188:189]
	s_mov_b32 m0, s0
	s_nop 0
	global_load_lds_dwordx4 v[180:181], off
	s_waitcnt vmcnt(8)
	s_waitcnt lgkmcnt(0)
	s_setprio 1
	s_barrier
	v_mfma_f32_16x16x32_bf16 v[62:65], v[136:139], v[168:171], v[62:65]
	v_mfma_f32_16x16x32_bf16 v[54:57], v[144:147], v[168:171], v[54:57]
	v_mfma_f32_16x16x32_bf16 v[46:49], v[136:139], v[176:179], v[46:49]
	v_mfma_f32_16x16x32_bf16 v[38:41], v[144:147], v[176:179], v[38:41]
	v_mfma_f32_16x16x32_bf16 v[30:33], v[136:139], v[204:207], v[30:33]
	v_mfma_f32_16x16x32_bf16 v[22:25], v[144:147], v[204:207], v[22:25]
	v_mfma_f32_16x16x32_bf16 v[14:17], v[136:139], v[212:215], v[14:17]
	v_mfma_f32_16x16x32_bf16 v[6:9], v[144:147], v[212:215], v[6:9]
	v_mfma_f32_16x16x32_bf16 v[62:65], v[140:143], v[172:175], v[62:65]
	v_mfma_f32_16x16x32_bf16 v[54:57], v[148:151], v[172:175], v[54:57]
	v_mfma_f32_16x16x32_bf16 v[46:49], v[140:143], v[200:203], v[46:49]
	v_mfma_f32_16x16x32_bf16 v[38:41], v[148:151], v[200:203], v[38:41]
	v_mfma_f32_16x16x32_bf16 v[30:33], v[140:143], v[208:211], v[30:33]
	v_mfma_f32_16x16x32_bf16 v[22:25], v[148:151], v[208:211], v[22:25]
	v_mfma_f32_16x16x32_bf16 v[14:17], v[140:143], v[244:247], v[14:17]
	v_mfma_f32_16x16x32_bf16 v[6:9], v[148:151], v[244:247], v[6:9]
	s_setprio 0
	s_setprio 1
	v_mfma_f32_16x16x32_bf16 v[58:61], v[152:155], v[168:171], v[58:61]
	v_mfma_f32_16x16x32_bf16 v[50:53], v[160:163], v[168:171], v[50:53]
	v_mfma_f32_16x16x32_bf16 v[42:45], v[152:155], v[176:179], v[42:45]
	v_mfma_f32_16x16x32_bf16 v[34:37], v[160:163], v[176:179], v[34:37]
	v_mfma_f32_16x16x32_bf16 v[26:29], v[152:155], v[204:207], v[26:29]
	v_mfma_f32_16x16x32_bf16 v[18:21], v[160:163], v[204:207], v[18:21]
	v_mfma_f32_16x16x32_bf16 v[10:13], v[152:155], v[212:215], v[10:13]
	v_mfma_f32_16x16x32_bf16 v[2:5], v[160:163], v[212:215], v[2:5]
	v_mfma_f32_16x16x32_bf16 v[58:61], v[156:159], v[172:175], v[58:61]
	v_mfma_f32_16x16x32_bf16 v[50:53], v[164:167], v[172:175], v[50:53]
	v_mfma_f32_16x16x32_bf16 v[42:45], v[156:159], v[200:203], v[42:45]
	v_mfma_f32_16x16x32_bf16 v[34:37], v[164:167], v[200:203], v[34:37]
	v_mfma_f32_16x16x32_bf16 v[26:29], v[156:159], v[208:211], v[26:29]
	v_mfma_f32_16x16x32_bf16 v[18:21], v[164:167], v[208:211], v[18:21]
	s_setprio 2
	s_barrier
	v_mfma_f32_16x16x32_bf16 v[10:13], v[156:159], v[244:247], v[10:13]
	v_mfma_f32_16x16x32_bf16 v[2:5], v[164:167], v[244:247], v[2:5]
	s_setprio 0
	s_add_u32 s39, s39, 0x10000
	s_addc_u32 s50, s50, 0
	s_branch .LBB0_508

; #define PG8_STAGE(bufoff, gbase, voff) do { _Pragma("unroll") for (int _i = 0; _i < 2; ++_i) \
;         __builtin_amdgcn_global_load_lds((const unsigned*)((const char*)(gbase) + (voff)[_i]), (PG8_LAS unsigned*)(lds + (bufoff) + ldsw + _i * 8192), 16, 0, 0); } while (0)
; #define PG8_LDA(dst, b, h) do { _Pragma("unroll") for (int m = 0; m < 4; ++m) _Pragma("unroll") for (int k = 0; k < 2; ++k) dst[m][k] = *(const PG8_LAS bf16x8*)(lds + PG8_SA(b, h) + aoff + m * 2048 + k * 1024); } while (0)
; #define PG8_LDB(dst, b, h) do { _Pragma("unroll") for (int n = 0; n < 2; ++n) _Pragma("unroll") for (int k = 0; k < 2; ++k) dst[n][k] = *(const PG8_LAS bf16x8*)(lds + PG8_SB(b, h) + boff + n * 2048 + k * 1024); } while (0)
; #define PG8_MMA(ai, bj, At, Bt) do { __builtin_amdgcn_s_setprio(1); _Pragma("unroll") for (int m = 0; m < 4; ++m) _Pragma("unroll") for (int n = 0; n < 2; ++n) _Pragma("unroll") for (int k = 0; k < 2; ++k) \
;         acc[ai][bj][m][n] = __builtin_amdgcn_mfma_f32_16x16x32_bf16(Bt[n][k], At[m][k], acc[ai][bj][m][n], 0, 0, 0); __builtin_amdgcn_s_setprio(0); } while (0)
; #define PG8_WAIT_V(n) asm volatile("s_waitcnt vmcnt(" #n ")" ::: "memory")
; template <class Epi, class Sched, bool ALIGN_EPI = false, bool SP2 = false>
; __device__ __forceinline__ void gemm_phase(PG8_LAS unsigned char* lds, const Gemm g, const Sched& S, const Epi& E) {
;     ...
;         for (int t = 0; t < nt; t += 2) {
;             const bool last = (t == nt - 2);
;             const char* a1 = cA + (size_t)(t + 1) * kstepA;
;             const char* a2 = last ? nA : cA + (size_t)(t + 2) * kstepA; const char* b2 = last ? nB : cB + (size_t)(t + 2) * kstepB;
;             const char* a3 = a2 + kstepA; const char* b3 = b2 + kstepB;
;             if (last && has_next) { S.a_ready(nxt); E.prefetch(nxt, ui + 1, tid); }
;             if constexpr (SP2) {
;             PG8_LDB(B0, 0, 0); PG8_LDB(B1, 0, 1); PG8_SCHED; PG8_LDA(At, 0, 0); PG8_STAGE(PG8_SA(1, 1), a1 + hstepA, voffA);
;             PG8_WAIT_V(8); PG8_WAIT_L(0); PG8_BAR; PG8_MMA(0, 0, At, B0); PG8_MMA(0, 1, At, B1); PG8_BAR; PG8_SCHED;
;             PG8_LDA(At, 0, 1); PG8_STAGE(PG8_SB(0, 0), b2, voffB); PG8_STAGE(PG8_SB(0, 1), b2 + hstepB, voffB); PG8_STAGE(PG8_SA(0, 0), a2, voffA);
;             PG8_WAIT_V(8); PG8_WAIT_L(0); PG8_BAR; PG8_MMA(1, 0, At, B0); PG8_MMA(1, 1, At, B1); PG8_BAR; PG8_SCHED;
.LBB0_507:
	s_add_u32 s18, s14, 1
	s_addc_u32 s19, s15, 0
	s_lshl_b64 s[60:61], s[18:19], s48
	s_add_u32 s14, s14, 2
	s_addc_u32 s15, s15, 0
	s_lshl_b64 s[18:19], s[14:15], s48
	s_add_u32 s18, s2, s18
	s_addc_u32 s19, s3, s19
	s_and_b64 s[16:17], s[16:17], exec
	s_cselect_b32 s24, s52, s18
	s_cselect_b32 s25, s53, s19
	s_cselect_b32 s19, s55, s50
	s_cselect_b32 s18, s54, s39
	s_add_u32 s16, s24, s35
	s_addc_u32 s17, s25, 0
	s_add_u32 s20, s18, 0x8000
	s_addc_u32 s21, s19, 0
	s_add_i32 s51, 0, 0x10000
	s_add_i32 s72, 0, 0x14000
	v_add_u32_e32 v148, s51, v195
	v_add_u32_e32 v164, s72, v195
	s_waitcnt lgkmcnt(0)
	ds_read_b128 v[136:139], v148
	ds_read_b128 v[140:143], v148 offset:1024
	ds_read_b128 v[144:147], v148 offset:2048
	ds_read_b128 v[148:151], v148 offset:3072
	ds_read_b128 v[152:155], v164
	ds_read_b128 v[156:159], v164 offset:1024
	ds_read_b128 v[160:163], v164 offset:2048
	ds_read_b128 v[164:167], v164 offset:3072
	s_add_u32 s60, s31, s60
	s_addc_u32 s61, s36, s61
	v_lshl_add_u64 v[180:181], s[60:61], 0, v[184:185]
	s_add_i32 m0, s63, 0xc000
	ds_read_b128 v[168:171], v242
	ds_read_b128 v[172:175], v242 offset:1024
	ds_read_b128 v[176:179], v242 offset:2048
	ds_read_b128 v[200:203], v242 offset:3072
	ds_read_b128 v[204:207], v242 offset:4096
	ds_read_b128 v[208:211], v242 offset:5120
	ds_read_b128 v[212:215], v242 offset:6144
	ds_read_b128 v[244:247], v242 offset:7168
	global_load_lds_dwordx4 v[180:181], off
	v_lshl_add_u64 v[180:181], s[60:61], 0, v[188:189]
	s_add_i32 m0, s63, 0xe000
	s_nop 0
	global_load_lds_dwordx4 v[180:181], off
	s_waitcnt vmcnt(8)
	s_waitcnt lgkmcnt(0)
	s_setprio 1
	s_barrier
	v_mfma_f32_16x16x32_bf16 v[126:129], v[136:139], v[168:171], v[126:129]
	v_mfma_f32_16x16x32_bf16 v[118:121], v[144:147], v[168:171], v[118:121]
	v_mfma_f32_16x16x32_bf16 v[110:113], v[136:139], v[176:179], v[110:113]
	v_mfma_f32_16x16x32_bf16 v[102:105], v[144:147], v[176:179], v[102:105]
	v_mfma_f32_16x16x32_bf16 v[94:97], v[136:139], v[204:207], v[94:97]
	v_mfma_f32_16x16x32_bf16 v[86:89], v[144:147], v[204:207], v[86:89]
	v_mfma_f32_16x16x32_bf16 v[78:81], v[136:139], v[212:215], v[78:81]
	v_mfma_f32_16x16x32_bf16 v[70:73], v[144:147], v[212:215], v[70:73]
	v_mfma_f32_16x16x32_bf16 v[126:129], v[140:143], v[172:175], v[126:129]
	v_mfma_f32_16x16x32_bf16 v[118:121], v[148:151], v[172:175], v[118:121]
	v_mfma_f32_16x16x32_bf16 v[110:113], v[140:143], v[200:203], v[110:113]
	v_mfma_f32_16x16x32_bf16 v[102:105], v[148:151], v[200:203], v[102:105]
	v_mfma_f32_16x16x32_bf16 v[94:97], v[140:143], v[208:211], v[94:97]
	v_mfma_f32_16x16x32_bf16 v[86:89], v[148:151], v[208:211], v[86:89]
	v_mfma_f32_16x16x32_bf16 v[78:81], v[140:143], v[244:247], v[78:81]
	v_mfma_f32_16x16x32_bf16 v[70:73], v[148:151], v[244:247], v[70:73]
	s_setprio 0
	s_setprio 1
	v_mfma_f32_16x16x32_bf16 v[122:125], v[152:155], v[168:171], v[122:125]
	v_mfma_f32_16x16x32_bf16 v[114:117], v[160:163], v[168:171], v[114:117]
	v_mfma_f32_16x16x32_bf16 v[106:109], v[152:155], v[176:179], v[106:109]
	v_mfma_f32_16x16x32_bf16 v[98:101], v[160:163], v[176:179], v[98:101]
	v_mfma_f32_16x16x32_bf16 v[90:93], v[152:155], v[204:207], v[90:93]
	v_mfma_f32_16x16x32_bf16 v[82:85], v[160:163], v[204:207], v[82:85]
	v_mfma_f32_16x16x32_bf16 v[74:77], v[152:155], v[212:215], v[74:77]
	v_mfma_f32_16x16x32_bf16 v[66:69], v[160:163], v[212:215], v[66:69]
	v_mfma_f32_16x16x32_bf16 v[122:125], v[156:159], v[172:175], v[122:125]
	v_mfma_f32_16x16x32_bf16 v[114:117], v[164:167], v[172:175], v[114:117]
	v_mfma_f32_16x16x32_bf16 v[106:109], v[156:159], v[200:203], v[106:109]
	v_mfma_f32_16x16x32_bf16 v[98:101], v[164:167], v[200:203], v[98:101]
	v_mfma_f32_16x16x32_bf16 v[90:93], v[156:159], v[208:211], v[90:93]
	v_mfma_f32_16x16x32_bf16 v[82:85], v[164:167], v[208:211], v[82:85]
	s_setprio 2
	s_barrier
	v_mfma_f32_16x16x32_bf16 v[74:77], v[156:159], v[244:247], v[74:77]
	v_mfma_f32_16x16x32_bf16 v[66:69], v[164:167], v[244:247], v[66:69]
	s_setprio 0
	s_add_i32 s51, s51, s62
	v_lshl_add_u64 v[180:181], s[18:19], 0, v[186:187]
	s_mov_b32 m0, s51
	ds_read_b128 v[168:171], v242 offset:16384
	ds_read_b128 v[172:175], v242 offset:17408
	ds_read_b128 v[176:179], v242 offset:18432
	ds_read_b128 v[200:203], v242 offset:19456
	ds_read_b128 v[204:207], v242 offset:20480
	ds_read_b128 v[208:211], v242 offset:21504
	ds_read_b128 v[212:215], v242 offset:22528
	ds_read_b128 v[244:247], v242 offset:23552
	global_load_lds_dwordx4 v[180:181], off
	s_add_i32 m0, s51, 0x2000
	s_add_u32 s60, s18, 0x4000
	v_lshl_add_u64 v[180:181], s[18:19], 0, v[190:191]
	s_addc_u32 s61, s19, 0
	s_add_i32 s51, s72, s62
	global_load_lds_dwordx4 v[180:181], off
	v_lshl_add_u64 v[180:181], s[60:61], 0, v[186:187]
	s_mov_b32 m0, s51
	s_nop 0
	global_load_lds_dwordx4 v[180:181], off
	v_lshl_add_u64 v[180:181], s[60:61], 0, v[190:191]
	s_add_i32 m0, s51, 0x2000
	s_nop 0
	global_load_lds_dwordx4 v[180:181], off
	v_lshl_add_u64 v[180:181], s[24:25], 0, v[184:185]
	s_mov_b32 m0, s63
	s_nop 0
	global_load_lds_dwordx4 v[180:181], off
	v_lshl_add_u64 v[180:181], s[24:25], 0, v[188:189]
	s_mov_b32 m0, s28
	s_nop 0
	global_load_lds_dwordx4 v[180:181], off
	s_waitcnt vmcnt(8)
	s_waitcnt lgkmcnt(0)
	s_setprio 1
	s_barrier
; #define PG8_STAGE(bufoff, gbase, voff) do { _Pragma("unroll") for (int _i = 0; _i < 2; ++_i) \
;         __builtin_amdgcn_global_load_lds((const unsigned*)((const char*)(gbase) + (voff)[_i]), (PG8_LAS unsigned*)(lds + (bufoff) + ldsw + _i * 8192), 16, 0, 0); } while (0)
; #define PG8_LDA(dst, b, h) do { _Pragma("unroll") for (int m = 0; m < 4; ++m) _Pragma("unroll") for (int k = 0; k < 2; ++k) dst[m][k] = *(const PG8_LAS bf16x8*)(lds + PG8_SA(b, h) + aoff + m * 2048 + k * 1024); } while (0)
; #define PG8_LDB(dst, b, h) do { _Pragma("unroll") for (int n = 0; n < 2; ++n) _Pragma("unroll") for (int k = 0; k < 2; ++k) dst[n][k] = *(const PG8_LAS bf16x8*)(lds + PG8_SB(b, h) + boff + n * 2048 + k * 1024); } while (0)
; #define PG8_MMA(ai, bj, At, Bt) do { __builtin_amdgcn_s_setprio(1); _Pragma("unroll") for (int m = 0; m < 4; ++m) _Pragma("unroll") for (int n = 0; n < 2; ++n) _Pragma("unroll") for (int k = 0; k < 2; ++k) \
;         acc[ai][bj][m][n] = __builtin_amdgcn_mfma_f32_16x16x32_bf16(Bt[n][k], At[m][k], acc[ai][bj][m][n], 0, 0, 0); __builtin_amdgcn_s_setprio(0); } while (0)
; #define PG8_WAIT_V(n) asm volatile("s_waitcnt vmcnt(" #n ")" ::: "memory")
; #define PG8_WAIT_L(n) asm volatile("s_waitcnt lgkmcnt(" #n ")" ::: "memory")
; #define PG8_BAR __builtin_amdgcn_s_barrier()
; #define PG8_SCHED __builtin_amdgcn_sched_barrier(0)
; template <class Epi, class Sched, bool ALIGN_EPI = false, bool SP2 = false>
; __device__ __forceinline__ void gemm_phase(PG8_LAS unsigned char* lds, const Gemm g, const Sched& S, const Epi& E) {
;     ...
;             PG8_WAIT_V(8); PG8_WAIT_L(0); PG8_BAR; PG8_MMA(1, 0, At, B0); PG8_MMA(1, 1, At, B1); PG8_BAR; PG8_SCHED;
;             PG8_LDB(B0, 1, 0); PG8_LDB(B1, 1, 1); PG8_SCHED; PG8_LDA(At, 1, 0); PG8_STAGE(PG8_SA(0, 1), a2 + hstepA, voffA);
;             PG8_WAIT_V(8); PG8_WAIT_L(0); PG8_BAR; PG8_MMA(0, 0, At, B0); PG8_MMA(0, 1, At, B1); PG8_BAR; PG8_SCHED;
	v_mfma_f32_16x16x32_bf16 v[62:65], v[136:139], v[168:171], v[62:65]
	v_mfma_f32_16x16x32_bf16 v[54:57], v[144:147], v[168:171], v[54:57]
	v_mfma_f32_16x16x32_bf16 v[46:49], v[136:139], v[176:179], v[46:49]
	v_mfma_f32_16x16x32_bf16 v[38:41], v[144:147], v[176:179], v[38:41]
	v_mfma_f32_16x16x32_bf16 v[30:33], v[136:139], v[204:207], v[30:33]
	v_mfma_f32_16x16x32_bf16 v[22:25], v[144:147], v[204:207], v[22:25]
	v_mfma_f32_16x16x32_bf16 v[14:17], v[136:139], v[212:215], v[14:17]
	v_mfma_f32_16x16x32_bf16 v[6:9], v[144:147], v[212:215], v[6:9]
	v_mfma_f32_16x16x32_bf16 v[62:65], v[140:143], v[172:175], v[62:65]
	v_mfma_f32_16x16x32_bf16 v[54:57], v[148:151], v[172:175], v[54:57]
	v_mfma_f32_16x16x32_bf16 v[46:49], v[140:143], v[200:203], v[46:49]
	v_mfma_f32_16x16x32_bf16 v[38:41], v[148:151], v[200:203], v[38:41]
	v_mfma_f32_16x16x32_bf16 v[30:33], v[140:143], v[208:211], v[30:33]
	v_mfma_f32_16x16x32_bf16 v[22:25], v[148:151], v[208:211], v[22:25]
	v_mfma_f32_16x16x32_bf16 v[14:17], v[140:143], v[244:247], v[14:17]
	v_mfma_f32_16x16x32_bf16 v[6:9], v[148:151], v[244:247], v[6:9]
	s_setprio 0
	s_setprio 1
	v_mfma_f32_16x16x32_bf16 v[58:61], v[152:155], v[168:171], v[58:61]
	v_mfma_f32_16x16x32_bf16 v[50:53], v[160:163], v[168:171], v[50:53]
	v_mfma_f32_16x16x32_bf16 v[42:45], v[152:155], v[176:179], v[42:45]
	v_mfma_f32_16x16x32_bf16 v[34:37], v[160:163], v[176:179], v[34:37]
	v_mfma_f32_16x16x32_bf16 v[26:29], v[152:155], v[204:207], v[26:29]
	v_mfma_f32_16x16x32_bf16 v[18:21], v[160:163], v[204:207], v[18:21]
	v_mfma_f32_16x16x32_bf16 v[10:13], v[152:155], v[212:215], v[10:13]
	v_mfma_f32_16x16x32_bf16 v[2:5], v[160:163], v[212:215], v[2:5]
	v_mfma_f32_16x16x32_bf16 v[58:61], v[156:159], v[172:175], v[58:61]
	v_mfma_f32_16x16x32_bf16 v[50:53], v[164:167], v[172:175], v[50:53]
	v_mfma_f32_16x16x32_bf16 v[42:45], v[156:159], v[200:203], v[42:45]
	v_mfma_f32_16x16x32_bf16 v[34:37], v[164:167], v[200:203], v[34:37]
	v_mfma_f32_16x16x32_bf16 v[26:29], v[156:159], v[208:211], v[26:29]
	v_mfma_f32_16x16x32_bf16 v[18:21], v[164:167], v[208:211], v[18:21]
	s_setprio 2
	s_barrier
	v_mfma_f32_16x16x32_bf16 v[10:13], v[156:159], v[244:247], v[10:13]
	v_mfma_f32_16x16x32_bf16 v[2:5], v[164:167], v[244:247], v[2:5]
	s_setprio 0
	s_add_i32 s51, 0, 0x18000
	s_add_i32 s60, 0, 0x1c000
	v_add_u32_e32 v148, s51, v195
	v_add_u32_e32 v164, s60, v195
	ds_read_b128 v[136:139], v148
	ds_read_b128 v[140:143], v148 offset:1024
	ds_read_b128 v[144:147], v148 offset:2048
	ds_read_b128 v[148:151], v148 offset:3072
	ds_read_b128 v[152:155], v164
	ds_read_b128 v[156:159], v164 offset:1024
	ds_read_b128 v[160:163], v164 offset:2048
	ds_read_b128 v[164:167], v164 offset:3072
	s_add_u32 s24, s24, s45
	s_addc_u32 s25, s25, s44
	s_mov_b32 m0, s29
	v_lshl_add_u64 v[180:181], s[24:25], 0, v[184:185]
	ds_read_b128 v[168:171], v242 offset:32768
	ds_read_b128 v[172:175], v242 offset:33792
	ds_read_b128 v[176:179], v242 offset:34816
	ds_read_b128 v[200:203], v242 offset:35840
	ds_read_b128 v[204:207], v242 offset:36864
	ds_read_b128 v[208:211], v242 offset:37888
	ds_read_b128 v[212:215], v242 offset:38912
	ds_read_b128 v[244:247], v242 offset:39936
	global_load_lds_dwordx4 v[180:181], off
	v_lshl_add_u64 v[180:181], s[24:25], 0, v[188:189]
	s_mov_b32 m0, s26
	s_nop 0
	global_load_lds_dwordx4 v[180:181], off
	s_waitcnt vmcnt(8)
	s_waitcnt lgkmcnt(0)
	s_setprio 1
	s_barrier
	v_mfma_f32_16x16x32_bf16 v[126:129], v[136:139], v[168:171], v[126:129]
	v_mfma_f32_16x16x32_bf16 v[118:121], v[144:147], v[168:171], v[118:121]
	v_mfma_f32_16x16x32_bf16 v[110:113], v[136:139], v[176:179], v[110:113]
	v_mfma_f32_16x16x32_bf16 v[102:105], v[144:147], v[176:179], v[102:105]
	v_mfma_f32_16x16x32_bf16 v[94:97], v[136:139], v[204:207], v[94:97]
	v_mfma_f32_16x16x32_bf16 v[86:89], v[144:147], v[204:207], v[86:89]
	v_mfma_f32_16x16x32_bf16 v[78:81], v[136:139], v[212:215], v[78:81]
	v_mfma_f32_16x16x32_bf16 v[70:73], v[144:147], v[212:215], v[70:73]
	v_mfma_f32_16x16x32_bf16 v[126:129], v[140:143], v[172:175], v[126:129]
	v_mfma_f32_16x16x32_bf16 v[118:121], v[148:151], v[172:175], v[118:121]
	v_mfma_f32_16x16x32_bf16 v[110:113], v[140:143], v[200:203], v[110:113]
	v_mfma_f32_16x16x32_bf16 v[102:105], v[148:151], v[200:203], v[102:105]
	v_mfma_f32_16x16x32_bf16 v[94:97], v[140:143], v[208:211], v[94:97]
	v_mfma_f32_16x16x32_bf16 v[86:89], v[148:151], v[208:211], v[86:89]
	v_mfma_f32_16x16x32_bf16 v[78:81], v[140:143], v[244:247], v[78:81]
	v_mfma_f32_16x16x32_bf16 v[70:73], v[148:151], v[244:247], v[70:73]
	s_setprio 0
	s_setprio 1
	v_mfma_f32_16x16x32_bf16 v[122:125], v[152:155], v[168:171], v[122:125]
	v_mfma_f32_16x16x32_bf16 v[114:117], v[160:163], v[168:171], v[114:117]
	v_mfma_f32_16x16x32_bf16 v[106:109], v[152:155], v[176:179], v[106:109]
	v_mfma_f32_16x16x32_bf16 v[98:101], v[160:163], v[176:179], v[98:101]
	v_mfma_f32_16x16x32_bf16 v[90:93], v[152:155], v[204:207], v[90:93]
	v_mfma_f32_16x16x32_bf16 v[82:85], v[160:163], v[204:207], v[82:85]
	v_mfma_f32_16x16x32_bf16 v[74:77], v[152:155], v[212:215], v[74:77]
	v_mfma_f32_16x16x32_bf16 v[66:69], v[160:163], v[212:215], v[66:69]
	v_mfma_f32_16x16x32_bf16 v[122:125], v[156:159], v[172:175], v[122:125]
	v_mfma_f32_16x16x32_bf16 v[114:117], v[164:167], v[172:175], v[114:117]
	v_mfma_f32_16x16x32_bf16 v[106:109], v[156:159], v[200:203], v[106:109]
	v_mfma_f32_16x16x32_bf16 v[98:101], v[164:167], v[200:203], v[98:101]
	v_mfma_f32_16x16x32_bf16 v[90:93], v[156:159], v[208:211], v[90:93]
	v_mfma_f32_16x16x32_bf16 v[82:85], v[164:167], v[208:211], v[82:85]
	s_setprio 2
	s_barrier
; #define PG8_STAGE(bufoff, gbase, voff) do { _Pragma("unroll") for (int _i = 0; _i < 2; ++_i) \
;         __builtin_amdgcn_global_load_lds((const unsigned*)((const char*)(gbase) + (voff)[_i]), (PG8_LAS unsigned*)(lds + (bufoff) + ldsw + _i * 8192), 16, 0, 0); } while (0)
; #define PG8_LDA(dst, b, h) do { _Pragma("unroll") for (int m = 0; m < 4; ++m) _Pragma("unroll") for (int k = 0; k < 2; ++k) dst[m][k] = *(const PG8_LAS bf16x8*)(lds + PG8_SA(b, h) + aoff + m * 2048 + k * 1024); } while (0)
; #define PG8_MMA(ai, bj, At, Bt) do { __builtin_amdgcn_s_setprio(1); _Pragma("unroll") for (int m = 0; m < 4; ++m) _Pragma("unroll") for (int n = 0; n < 2; ++n) _Pragma("unroll") for (int k = 0; k < 2; ++k) \
;         acc[ai][bj][m][n] = __builtin_amdgcn_mfma_f32_16x16x32_bf16(Bt[n][k], At[m][k], acc[ai][bj][m][n], 0, 0, 0); __builtin_amdgcn_s_setprio(0); } while (0)
; #define PG8_WAIT_V(n) asm volatile("s_waitcnt vmcnt(" #n ")" ::: "memory")
; #define PG8_WAIT_L(n) asm volatile("s_waitcnt lgkmcnt(" #n ")" ::: "memory")
; #define PG8_BAR __builtin_amdgcn_s_barrier()
; #define PG8_SCHED __builtin_amdgcn_sched_barrier(0)
; template <class Epi, class Sched, bool ALIGN_EPI = false, bool SP2 = false>
; __device__ __forceinline__ void gemm_phase(PG8_LAS unsigned char* lds, const Gemm g, const Sched& S, const Epi& E) {
;     ...
;             PG8_WAIT_V(8); PG8_WAIT_L(0); PG8_BAR; PG8_MMA(0, 0, At, B0); PG8_MMA(0, 1, At, B1); PG8_BAR; PG8_SCHED;
;             PG8_LDA(At, 1, 1); PG8_STAGE(PG8_SB(1, 0), b3, voffB); PG8_STAGE(PG8_SB(1, 1), b3 + hstepB, voffB); PG8_STAGE(PG8_SA(1, 0), a3, voffA);
;             PG8_WAIT_V(8); PG8_WAIT_L(0); PG8_BAR; PG8_MMA(1, 0, At, B0); PG8_MMA(1, 1, At, B1); PG8_BAR; PG8_SCHED;
	v_mfma_f32_16x16x32_bf16 v[74:77], v[156:159], v[244:247], v[74:77]
	v_mfma_f32_16x16x32_bf16 v[66:69], v[164:167], v[244:247], v[66:69]
	s_setprio 0
	s_add_i32 s24, s51, s62
	v_lshl_add_u64 v[180:181], s[20:21], 0, v[186:187]
	s_mov_b32 m0, s24
	ds_read_b128 v[168:171], v242 offset:49152
	ds_read_b128 v[172:175], v242 offset:50176
	ds_read_b128 v[176:179], v242 offset:51200
	ds_read_b128 v[200:203], v242 offset:52224
	ds_read_b128 v[204:207], v242 offset:53248
	ds_read_b128 v[208:211], v242 offset:54272
	ds_read_b128 v[212:215], v242 offset:55296
	ds_read_b128 v[244:247], v242 offset:56320
	global_load_lds_dwordx4 v[180:181], off
	s_add_i32 m0, s24, 0x2000
	s_add_u32 s18, s18, 0xc000
	v_lshl_add_u64 v[180:181], s[20:21], 0, v[190:191]
	s_addc_u32 s19, s19, 0
	s_add_i32 s20, s60, s62
	global_load_lds_dwordx4 v[180:181], off
	v_lshl_add_u64 v[180:181], s[18:19], 0, v[186:187]
	s_mov_b32 m0, s20
	s_nop 0
	global_load_lds_dwordx4 v[180:181], off
	v_lshl_add_u64 v[180:181], s[18:19], 0, v[190:191]
	s_add_i32 m0, s20, 0x2000
	s_nop 0
	global_load_lds_dwordx4 v[180:181], off
	v_lshl_add_u64 v[180:181], s[16:17], 0, v[184:185]
	s_mov_b32 m0, s1
	s_nop 0
	global_load_lds_dwordx4 v[180:181], off
	v_lshl_add_u64 v[180:181], s[16:17], 0, v[188:189]
	s_mov_b32 m0, s0
	s_nop 0
	global_load_lds_dwordx4 v[180:181], off
	s_waitcnt vmcnt(8)
	s_waitcnt lgkmcnt(0)
	s_setprio 1
	s_barrier
	v_mfma_f32_16x16x32_bf16 v[62:65], v[136:139], v[168:171], v[62:65]
	v_mfma_f32_16x16x32_bf16 v[54:57], v[144:147], v[168:171], v[54:57]
	v_mfma_f32_16x16x32_bf16 v[46:49], v[136:139], v[176:179], v[46:49]
	v_mfma_f32_16x16x32_bf16 v[38:41], v[144:147], v[176:179], v[38:41]
	v_mfma_f32_16x16x32_bf16 v[30:33], v[136:139], v[204:207], v[30:33]
	v_mfma_f32_16x16x32_bf16 v[22:25], v[144:147], v[204:207], v[22:25]
	v_mfma_f32_16x16x32_bf16 v[14:17], v[136:139], v[212:215], v[14:17]
	v_mfma_f32_16x16x32_bf16 v[6:9], v[144:147], v[212:215], v[6:9]
	v_mfma_f32_16x16x32_bf16 v[62:65], v[140:143], v[172:175], v[62:65]
	v_mfma_f32_16x16x32_bf16 v[54:57], v[148:151], v[172:175], v[54:57]
	v_mfma_f32_16x16x32_bf16 v[46:49], v[140:143], v[200:203], v[46:49]
	v_mfma_f32_16x16x32_bf16 v[38:41], v[148:151], v[200:203], v[38:41]
	v_mfma_f32_16x16x32_bf16 v[30:33], v[140:143], v[208:211], v[30:33]
	v_mfma_f32_16x16x32_bf16 v[22:25], v[148:151], v[208:211], v[22:25]
	v_mfma_f32_16x16x32_bf16 v[14:17], v[140:143], v[244:247], v[14:17]
	v_mfma_f32_16x16x32_bf16 v[6:9], v[148:151], v[244:247], v[6:9]
	s_setprio 0
	s_setprio 1
	v_mfma_f32_16x16x32_bf16 v[58:61], v[152:155], v[168:171], v[58:61]
	v_mfma_f32_16x16x32_bf16 v[50:53], v[160:163], v[168:171], v[50:53]
	v_mfma_f32_16x16x32_bf16 v[42:45], v[152:155], v[176:179], v[42:45]
	v_mfma_f32_16x16x32_bf16 v[34:37], v[160:163], v[176:179], v[34:37]
	v_mfma_f32_16x16x32_bf16 v[26:29], v[152:155], v[204:207], v[26:29]
	v_mfma_f32_16x16x32_bf16 v[18:21], v[160:163], v[204:207], v[18:21]
	v_mfma_f32_16x16x32_bf16 v[10:13], v[152:155], v[212:215], v[10:13]
	v_mfma_f32_16x16x32_bf16 v[2:5], v[160:163], v[212:215], v[2:5]
	v_mfma_f32_16x16x32_bf16 v[58:61], v[156:159], v[172:175], v[58:61]
	v_mfma_f32_16x16x32_bf16 v[50:53], v[164:167], v[172:175], v[50:53]
	v_mfma_f32_16x16x32_bf16 v[42:45], v[156:159], v[200:203], v[42:45]
	v_mfma_f32_16x16x32_bf16 v[34:37], v[164:167], v[200:203], v[34:37]
	v_mfma_f32_16x16x32_bf16 v[26:29], v[156:159], v[208:211], v[26:29]
	v_mfma_f32_16x16x32_bf16 v[18:21], v[164:167], v[208:211], v[18:21]
	s_setprio 2
	s_barrier
	v_mfma_f32_16x16x32_bf16 v[10:13], v[156:159], v[244:247], v[10:13]
	v_mfma_f32_16x16x32_bf16 v[2:5], v[164:167], v[244:247], v[2:5]
	s_setprio 0
	s_add_u32 s39, s39, 0x10000
	s_addc_u32 s50, s50, 0
	s_cmp_ge_u32 s14, s34
	s_cbranch_scc1 .LBB0_518
